# counted lgkmcnt waits also in the post-loop PV MFMA blocks of both attention calls (three blocks)
# speedup vs baseline: 1.0068x; 1.0068x over previous
; #define SBAR() __builtin_amdgcn_sched_barrier(0)
; template <int OFF> __device__ __forceinline__ s16x4 tr_read(int vb) { s16x4 r; asm volatile("ds_read_b64_tr_b16 %0, %1 offset:%2" : "=&v"(r) : "v"(vb), "i"(OFF) : "memory"); return r; }
; template <int D0> __device__ __forceinline__ void pv_one(f32x16& od, int vb, bf16x8 pa0, bf16x8 pa1, bf16x8 pa2, bf16x8 pa3) {
;     const s16x4 l0 = tr_read<v_rd_off(D0, 0, 0)>(vb), h0 = tr_read<v_rd_off(D0, 0, 1)>(vb), l1 = tr_read<v_rd_off(D0, 1, 0)>(vb), h1 = tr_read<v_rd_off(D0, 1, 1)>(vb);
;     const s16x4 l2 = tr_read<v_rd_off(D0, 2, 0)>(vb), h2 = tr_read<v_rd_off(D0, 2, 1)>(vb), l3 = tr_read<v_rd_off(D0, 3, 0)>(vb), h3 = tr_read<v_rd_off(D0, 3, 1)>(vb);
;     asm volatile("s_waitcnt lgkmcnt(0)" ::: "memory"); SBAR();
;     ...
;     od = __builtin_amdgcn_mfma_f32_32x32x16_bf16(pa0, PK(l0, h0), od, 0, 0, 0);
;     od = __builtin_amdgcn_mfma_f32_32x32x16_bf16(pa1, PK(l1, h1), od, 0, 0, 0);
;     od = __builtin_amdgcn_mfma_f32_32x32x16_bf16(pa2, PK(l2, h2), od, 0, 0, 0);
;     od = __builtin_amdgcn_mfma_f32_32x32x16_bf16(pa3, PK(l3, h3), od, 0, 0, 0);
;     ...
; }
; __device__ __forceinline__ void pv_d0(f32x16* o, int vb, bf16x8 pa0, bf16x8 pa1, bf16x8 pa2, bf16x8 pa3) {
;     pv_one<0>(o[0], vb, pa0, pa1, pa2, pa3); pv_one<1>(o[1], vb, pa0, pa1, pa2, pa3); pv_one<2>(o[2], vb, pa0, pa1, pa2, pa3); pv_one<3>(o[3], vb, pa0, pa1, pa2, pa3);
; template <int DQK, int DK1, int LDQ, int LDK, int LDKR, int LDV, int NQL, int SDEPTH>
; __device__ __forceinline__ void attn_core(const AttnArgs& a, char* lds, f32x16 (&o)[4]) {
;     ...
;     SBAR(); QKT(pB0, pB1, K_lds + SHM_K);
;     finishSM(pA0, pA1, alA, l_reg, pa0, pa1, pa2, pa3); SBAR();
;     pv_d0(o, vb0, pa0, pa1, pa2, pa3); partialSM(pB0, pB1, m_reg, mnB, alB, a.C, a.thr);
.LBB0_183:
	ds_read_b128 v[64:67], v186 offset:40960
	ds_read_b128 v[68:71], v186 offset:45056
	v_exp_f32_e32 v118, v140
	v_exp_f32_e32 v119, v141
	v_exp_f32_e32 v120, v134
	s_waitcnt lgkmcnt(1)
	v_mfma_f32_32x32x16_bf16 v[80:95], v[64:67], v[110:113], 0
	v_exp_f32_e32 v121, v135
	v_exp_f32_e32 v122, v132
	v_exp_f32_e32 v123, v133
	s_waitcnt lgkmcnt(0)
	v_mfma_f32_32x32x16_bf16 v[64:79], v[68:71], v[110:113], 0
	ds_read_b128 v[110:113], v188 offset:40960
	ds_read_b128 v[114:117], v188 offset:45056
	s_waitcnt lgkmcnt(1)
	v_mfma_f32_32x32x16_bf16 v[80:95], v[110:113], v[106:109], v[80:95]
	s_waitcnt lgkmcnt(0)
	v_mfma_f32_32x32x16_bf16 v[64:79], v[114:117], v[106:109], v[64:79]
	ds_read_b128 v[106:109], v190 offset:40960
	ds_read_b128 v[110:113], v190 offset:45056
	v_exp_f32_e32 v114, v128
	v_exp_f32_e32 v115, v129
	v_exp_f32_e32 v116, v126
	v_exp_f32_e32 v117, v127
	s_waitcnt lgkmcnt(1)
	v_mfma_f32_32x32x16_bf16 v[80:95], v[106:109], v[102:105], v[80:95]
	s_waitcnt lgkmcnt(0)
	v_mfma_f32_32x32x16_bf16 v[64:79], v[110:113], v[102:105], v[64:79]
	ds_read_b128 v[102:105], v192 offset:40960
	ds_read_b128 v[106:109], v192 offset:45056
	v_exp_f32_e32 v110, v136
	v_exp_f32_e32 v111, v137
	v_exp_f32_e32 v112, v130
	v_exp_f32_e32 v113, v131
	s_waitcnt lgkmcnt(1)
	v_mfma_f32_32x32x16_bf16 v[80:95], v[102:105], v[98:101], v[80:95]
	s_waitcnt lgkmcnt(0)
	v_mfma_f32_32x32x16_bf16 v[64:79], v[106:109], v[98:101], v[64:79]
	v_add_f32_e32 v98, 0, v217
	v_add_f32_e32 v98, v219, v98
	v_add_f32_e32 v98, v208, v98
	v_add_f32_e32 v98, v218, v98
	v_add_f32_e32 v98, v153, v98
	v_add_f32_e32 v98, v216, v98
	v_add_f32_e32 v98, v152, v98
	v_add_f32_e32 v98, v202, v98
	v_add_f32_e32 v98, v149, v98
	v_add_f32_e32 v98, v151, v98
	v_add_f32_e32 v98, v147, v98
	v_add_f32_e32 v98, v150, v98
	v_exp_f32_e32 v108, v138
	v_add_f32_e32 v98, v145, v98
	v_exp_f32_e32 v109, v139
	v_add_f32_e32 v98, v148, v98
	v_add_f32_e32 v98, v144, v98
	v_add_f32_e32 v98, v146, v98
	v_add_f32_e32 v98, v108, v98
	v_add_f32_e32 v98, v109, v98
	v_add_f32_e32 v98, v110, v98
	v_add_f32_e32 v98, v111, v98
	v_add_f32_e32 v98, v112, v98
	v_add_f32_e32 v98, v113, v98
	v_add_f32_e32 v98, v114, v98
	v_add_f32_e32 v98, v115, v98
	v_add_f32_e32 v98, v116, v98
	v_add_f32_e32 v98, v117, v98
	v_add_f32_e32 v98, v118, v98
	v_add_f32_e32 v98, v119, v98
	v_add_f32_e32 v98, v120, v98
	v_add_f32_e32 v98, v121, v98
	v_add_f32_e32 v98, v122, v98
	v_add_f32_e32 v98, v123, v98
	v_mov_b32_e32 v99, v98
	v_cvt_pk_bf16_f32 v100, v217, v219
	v_cvt_pk_bf16_f32 v101, v208, v218
	v_cvt_pk_bf16_f32 v102, v153, v216
	v_cvt_pk_bf16_f32 v103, v152, v202
	s_nop 1
	v_permlane32_swap_b32_e32 v98, v99
	v_permlane32_swap_b32_e32 v100, v102
	v_permlane32_swap_b32_e32 v101, v103
	v_cvt_pk_bf16_f32 v104, v149, v151
	v_cvt_pk_bf16_f32 v105, v147, v150
	v_cvt_pk_bf16_f32 v106, v145, v148
	v_cvt_pk_bf16_f32 v107, v144, v146
	v_cvt_pk_bf16_f32 v108, v108, v109
	v_cvt_pk_bf16_f32 v109, v110, v111
	v_cvt_pk_bf16_f32 v110, v112, v113
	v_cvt_pk_bf16_f32 v111, v114, v115
	v_cvt_pk_bf16_f32 v112, v116, v117
	v_cvt_pk_bf16_f32 v113, v118, v119
	v_cvt_pk_bf16_f32 v114, v120, v121
	v_cvt_pk_bf16_f32 v115, v122, v123
	s_nop 0
	v_permlane32_swap_b32_e32 v104, v106
	v_permlane32_swap_b32_e32 v105, v107
	v_permlane32_swap_b32_e32 v108, v110
	v_permlane32_swap_b32_e32 v109, v111
	v_permlane32_swap_b32_e32 v112, v114
	v_permlane32_swap_b32_e32 v113, v115
	ds_read_b64_tr_b16 v[116:117], v180 offset:0
	ds_read_b64_tr_b16 v[118:119], v180 offset:0x800
	ds_read_b64_tr_b16 v[120:121], v180 offset:0x1000
	ds_read_b64_tr_b16 v[122:123], v180 offset:0x1800
	ds_read_b64_tr_b16 v[124:125], v180 offset:0x2000
	ds_read_b64_tr_b16 v[126:127], v180 offset:0x2800
	ds_read_b64_tr_b16 v[128:129], v180 offset:0x3000
	ds_read_b64_tr_b16 v[130:131], v180 offset:0x3800
	s_waitcnt lgkmcnt(0)
	s_nop 0
	v_mfma_f32_32x32x16_bf16 v[48:63], v[100:103], v[116:119], v[48:63]
	ds_read_b64_tr_b16 v[116:117], v180 offset:0x200
	ds_read_b64_tr_b16 v[118:119], v180 offset:0xa00
	v_mfma_f32_32x32x16_bf16 v[48:63], v[104:107], v[120:123], v[48:63]
	ds_read_b64_tr_b16 v[120:121], v180 offset:0x1200
	ds_read_b64_tr_b16 v[122:123], v180 offset:0x1a00
	v_mfma_f32_32x32x16_bf16 v[48:63], v[108:111], v[124:127], v[48:63]
	ds_read_b64_tr_b16 v[124:125], v180 offset:0x2200
	ds_read_b64_tr_b16 v[126:127], v180 offset:0x2a00
	v_mfma_f32_32x32x16_bf16 v[48:63], v[112:115], v[128:131], v[48:63]
	ds_read_b64_tr_b16 v[128:129], v180 offset:0x3200
	ds_read_b64_tr_b16 v[130:131], v180 offset:0x3a00
	s_waitcnt lgkmcnt(6)
	v_mfma_f32_32x32x16_bf16 v[32:47], v[100:103], v[116:119], v[32:47]
	ds_read_b64_tr_b16 v[116:117], v180 offset:0x400
	ds_read_b64_tr_b16 v[118:119], v180 offset:0xc00
	s_waitcnt lgkmcnt(6)
; #define RESC(al) do { if (__any((al) < 1.f)) { if (hi == 0) al_l[r32] = (al); asm volatile("s_waitcnt lgkmcnt(0)" ::: "memory"); \
;     _Pragma("unroll") for (int d = 0; d < 4; ++d) _Pragma("unroll") for (int r = 0; r < 16; ++r) o[d][r] *= al_l[crow(r, hi)]; } } while (0)
; __device__ __forceinline__ void partialSM(f32x16& p0, f32x16& p1, float& m_reg, float& mn, float& alpha, const float C, const float thr) {
;     float pmax = p0[0];
; #pragma unroll
;     for (int r = 1; r < 16; ++r) pmax = fmaxf(pmax, p0[r]);
; #pragma unroll
;     for (int r = 0; r < 16; ++r) pmax = fmaxf(pmax, p1[r]);
;     { auto rr = __builtin_amdgcn_permlane32_swap(__float_as_uint(pmax), __float_as_uint(pmax), false, false);
;       pmax = fmaxf(__uint_as_float(rr[0]), __uint_as_float(rr[1])); }
;     if (__builtin_expect(__all(pmax - m_reg <= thr), 1)) { mn = m_reg; alpha = 1.f; }
;     else { mn = fmaxf(m_reg, pmax); alpha = __builtin_amdgcn_exp2f((m_reg - mn) * C); m_reg = mn; }
; template <int DQK, int DK1, int LDQ, int LDK, int LDKR, int LDV, int NQL, int SDEPTH>
; __device__ __forceinline__ void attn_core(const AttnArgs& a, char* lds, f32x16 (&o)[4]) {
;     ...
;     pv_d0(o, vb0, pa0, pa1, pa2, pa3); partialSM(pB0, pB1, m_reg, mnB, alB, a.C, a.thr);
;     __syncthreads(); RESC(alB);
	v_mfma_f32_32x32x16_bf16 v[32:47], v[104:107], v[120:123], v[32:47]
	ds_read_b64_tr_b16 v[120:121], v180 offset:0x1400
	ds_read_b64_tr_b16 v[122:123], v180 offset:0x1c00
	s_waitcnt lgkmcnt(6)
	v_mfma_f32_32x32x16_bf16 v[32:47], v[108:111], v[124:127], v[32:47]
	ds_read_b64_tr_b16 v[124:125], v180 offset:0x2400
	ds_read_b64_tr_b16 v[126:127], v180 offset:0x2c00
	s_waitcnt lgkmcnt(6)
	v_mfma_f32_32x32x16_bf16 v[32:47], v[112:115], v[128:131], v[32:47]
	ds_read_b64_tr_b16 v[128:129], v180 offset:0x3400
	ds_read_b64_tr_b16 v[130:131], v180 offset:0x3c00
	s_waitcnt lgkmcnt(6)
	v_mfma_f32_32x32x16_bf16 v[16:31], v[100:103], v[116:119], v[16:31]
	ds_read_b64_tr_b16 v[116:117], v180 offset:0x600
	ds_read_b64_tr_b16 v[118:119], v180 offset:0xe00
	s_waitcnt lgkmcnt(6)
	v_mfma_f32_32x32x16_bf16 v[16:31], v[104:107], v[120:123], v[16:31]
	ds_read_b64_tr_b16 v[120:121], v180 offset:0x1600
	ds_read_b64_tr_b16 v[122:123], v180 offset:0x1e00
	s_waitcnt lgkmcnt(6)
	v_mfma_f32_32x32x16_bf16 v[16:31], v[108:111], v[124:127], v[16:31]
	ds_read_b64_tr_b16 v[124:125], v180 offset:0x2600
	ds_read_b64_tr_b16 v[126:127], v180 offset:0x2e00
	s_waitcnt lgkmcnt(6)
	v_mfma_f32_32x32x16_bf16 v[16:31], v[112:115], v[128:131], v[16:31]
	ds_read_b64_tr_b16 v[128:129], v180 offset:0x3600
	ds_read_b64_tr_b16 v[130:131], v180 offset:0x3e00
	s_waitcnt lgkmcnt(6)
	v_mfma_f32_32x32x16_bf16 v[0:15], v[100:103], v[116:119], v[0:15]
	v_max_f32_e32 v100, v81, v81
	v_max_f32_e32 v101, v80, v80
	v_max_f32_e32 v100, v101, v100
	v_max3_f32 v100, v100, v82, v83
	v_max3_f32 v100, v100, v84, v85
	v_max3_f32 v100, v100, v86, v87
	v_max3_f32 v100, v100, v88, v89
	v_max3_f32 v100, v100, v90, v91
	v_max3_f32 v100, v100, v92, v93
	s_waitcnt lgkmcnt(4)
	v_mfma_f32_32x32x16_bf16 v[0:15], v[104:107], v[120:123], v[0:15]
	v_max3_f32 v100, v100, v94, v95
	v_max3_f32 v100, v100, v64, v65
	v_max3_f32 v100, v100, v66, v67
	v_max3_f32 v100, v100, v68, v69
	v_max3_f32 v100, v100, v70, v71
	v_max3_f32 v100, v100, v72, v73
	v_max3_f32 v100, v100, v74, v75
	v_max3_f32 v100, v100, v76, v77
	s_waitcnt lgkmcnt(2)
	v_mfma_f32_32x32x16_bf16 v[0:15], v[108:111], v[124:127], v[0:15]
	v_max3_f32 v100, v100, v78, v79
	v_mov_b32_e32 v101, v100
	s_nop 1
	v_permlane32_swap_b32_e32 v100, v101
	v_max_f32_e32 v101, v101, v101
	v_max_f32_e32 v100, v100, v100
	v_max_f32_e32 v100, v100, v101
	v_sub_f32_e32 v101, v100, v142
	v_cmp_ge_f32_e32 vcc, s76, v101
	v_max_f32_e32 v101, v142, v142
	v_max_f32_e32 v101, v101, v100
	s_waitcnt lgkmcnt(0)
	v_mfma_f32_32x32x16_bf16 v[0:15], v[112:115], v[128:131], v[0:15]
	v_sub_f32_e32 v100, v142, v101
	v_mul_f32_e32 v100, 0x3e38aa3b, v100
	v_exp_f32_e32 v100, v100
	s_cmp_eq_u64 vcc, exec
	s_cselect_b64 s[14:15], -1, 0
	v_cndmask_b32_e64 v100, v100, 1.0, s[14:15]
	v_cmp_gt_f32_e32 vcc, 1.0, v100
	s_barrier
	s_cbranch_vccz .LBB0_187
	s_and_saveexec_b64 s[38:39], s[12:13]
	ds_write_b32 v177, v100 offset:49280
	s_or_b64 exec, exec, s[38:39]
	s_waitcnt lgkmcnt(0)
	v_add_u32_e32 v114, v161, v96
	ds_read_b128 v[102:105], v114 offset:49376
	ds_read_b128 v[106:109], v114 offset:49344
	ds_read_b128 v[110:113], v114 offset:49312
	ds_read_b128 v[114:117], v114 offset:49280
	s_waitcnt lgkmcnt(3)
	v_pk_mul_f32 v[60:61], v[60:61], v[102:103]
	s_waitcnt lgkmcnt(2)
	v_pk_mul_f32 v[56:57], v[56:57], v[106:107]
	s_waitcnt lgkmcnt(1)
	v_pk_mul_f32 v[52:53], v[52:53], v[110:111]
	v_pk_mul_f32 v[62:63], v[62:63], v[104:105]
	v_pk_mul_f32 v[58:59], v[58:59], v[108:109]
	v_pk_mul_f32 v[54:55], v[54:55], v[112:113]
	s_waitcnt lgkmcnt(0)
	v_pk_mul_f32 v[50:51], v[50:51], v[116:117]
	v_pk_mul_f32 v[48:49], v[48:49], v[114:115]
	v_pk_mul_f32 v[44:45], v[44:45], v[102:103]
	v_pk_mul_f32 v[40:41], v[40:41], v[106:107]
	v_pk_mul_f32 v[36:37], v[36:37], v[110:111]
	v_pk_mul_f32 v[46:47], v[46:47], v[104:105]
	v_pk_mul_f32 v[42:43], v[42:43], v[108:109]
	v_pk_mul_f32 v[38:39], v[38:39], v[112:113]
	v_pk_mul_f32 v[34:35], v[34:35], v[116:117]
	v_pk_mul_f32 v[32:33], v[32:33], v[114:115]
	v_pk_mul_f32 v[28:29], v[28:29], v[102:103]
	v_pk_mul_f32 v[24:25], v[24:25], v[106:107]
	v_pk_mul_f32 v[20:21], v[20:21], v[110:111]
	v_pk_mul_f32 v[30:31], v[30:31], v[104:105]
	v_pk_mul_f32 v[26:27], v[26:27], v[108:109]
	v_pk_mul_f32 v[22:23], v[22:23], v[112:113]
	v_pk_mul_f32 v[18:19], v[18:19], v[116:117]
	v_pk_mul_f32 v[16:17], v[16:17], v[114:115]
	v_pk_mul_f32 v[12:13], v[12:13], v[102:103]
	v_pk_mul_f32 v[8:9], v[8:9], v[106:107]
	v_pk_mul_f32 v[4:5], v[4:5], v[110:111]
	v_pk_mul_f32 v[14:15], v[14:15], v[104:105]
	v_pk_mul_f32 v[10:11], v[10:11], v[108:109]
	v_pk_mul_f32 v[6:7], v[6:7], v[112:113]
	v_pk_mul_f32 v[2:3], v[2:3], v[116:117]
	v_pk_mul_f32 v[0:1], v[0:1], v[114:115]

; #define SBAR() __builtin_amdgcn_sched_barrier(0)
; template <int DQK, int DK1, int LDQ, int LDK, int LDKR, int LDV, int NQL, int SDEPTH>
; __device__ __forceinline__ void attn_core(const AttnArgs& a, char* lds, f32x16 (&o)[4]) {
;     ...
;     SBAR(); QKT(pB0, pB1, K_lds + SHM_K);
;     finishSM(pA0, pA1, alA, l_reg, pa0, pa1, pa2, pa3); SBAR();
.LBB0_229:
	ds_read_b128 v[64:67], v184 offset:57344
	ds_read_b128 v[68:71], v216 offset:12288
	s_waitcnt lgkmcnt(1)
	v_mfma_f32_32x32x16_bf16 v[80:95], v[64:67], v[126:129], 0
	s_waitcnt lgkmcnt(0)
	v_mfma_f32_32x32x16_bf16 v[64:79], v[68:71], v[126:129], 0
	ds_read_b128 v[126:129], v192 offset:57344
	ds_read_b128 v[174:177], v208 offset:12288
	s_waitcnt lgkmcnt(1)
	v_mfma_f32_32x32x16_bf16 v[80:95], v[126:129], v[122:125], v[80:95]
	s_waitcnt lgkmcnt(0)
	v_mfma_f32_32x32x16_bf16 v[64:79], v[174:177], v[122:125], v[64:79]
	ds_read_b128 v[122:125], v190 offset:57344
	ds_read_b128 v[126:129], v206 offset:12288
	s_waitcnt lgkmcnt(1)
	v_mfma_f32_32x32x16_bf16 v[80:95], v[122:125], v[118:121], v[80:95]
	s_waitcnt lgkmcnt(0)
	v_mfma_f32_32x32x16_bf16 v[64:79], v[126:129], v[118:121], v[64:79]
	ds_read_b128 v[118:121], v173 offset:57344
	ds_read_b128 v[122:125], v202 offset:12288
	s_waitcnt lgkmcnt(1)
	v_mfma_f32_32x32x16_bf16 v[80:95], v[118:121], v[114:117], v[80:95]
	s_waitcnt lgkmcnt(0)
	v_mfma_f32_32x32x16_bf16 v[64:79], v[122:125], v[114:117], v[64:79]
	ds_read_b128 v[114:117], v184 offset:57472
	ds_read_b128 v[118:121], v216 offset:12416
	v_exp_f32_e32 v122, v136
	v_exp_f32_e32 v123, v137
	s_waitcnt lgkmcnt(1)
	v_mfma_f32_32x32x16_bf16 v[80:95], v[114:117], v[110:113], v[80:95]
	s_waitcnt lgkmcnt(0)
	v_mfma_f32_32x32x16_bf16 v[64:79], v[118:121], v[110:113], v[64:79]
	ds_read_b128 v[110:113], v192 offset:57472
	ds_read_b128 v[114:117], v208 offset:12416
	v_exp_f32_e32 v118, v144
	v_exp_f32_e32 v119, v145
	v_exp_f32_e32 v120, v138
	v_exp_f32_e32 v121, v139
	s_waitcnt lgkmcnt(1)
	v_mfma_f32_32x32x16_bf16 v[80:95], v[110:113], v[106:109], v[80:95]
	s_waitcnt lgkmcnt(0)
	v_mfma_f32_32x32x16_bf16 v[64:79], v[114:117], v[106:109], v[64:79]
	ds_read_b128 v[106:109], v190 offset:57472
	ds_read_b128 v[110:113], v206 offset:12416
	v_exp_f32_e32 v114, v132
	v_exp_f32_e32 v115, v133
	v_exp_f32_e32 v116, v130
	v_exp_f32_e32 v117, v131
	s_waitcnt lgkmcnt(1)
	v_mfma_f32_32x32x16_bf16 v[80:95], v[106:109], v[102:105], v[80:95]
	s_waitcnt lgkmcnt(0)
	v_mfma_f32_32x32x16_bf16 v[64:79], v[110:113], v[102:105], v[64:79]
	ds_read_b128 v[102:105], v173 offset:57472
	ds_read_b128 v[106:109], v202 offset:12416
	v_exp_f32_e32 v110, v140
	v_exp_f32_e32 v111, v141
	v_exp_f32_e32 v112, v134
	v_exp_f32_e32 v113, v135
	s_waitcnt lgkmcnt(1)
	v_mfma_f32_32x32x16_bf16 v[80:95], v[102:105], v[98:101], v[80:95]
	s_waitcnt lgkmcnt(0)
	v_mfma_f32_32x32x16_bf16 v[64:79], v[106:109], v[98:101], v[64:79]
	ds_read_b128 v[98:101], v184 offset:57600
	ds_read_b128 v[102:105], v216 offset:12544
	ds_read_b128 v[106:109], v181
	s_waitcnt lgkmcnt(0)
	v_mfma_f32_32x32x16_bf16 v[80:95], v[98:101], v[106:109], v[80:95]
	v_mfma_f32_32x32x16_bf16 v[64:79], v[102:105], v[106:109], v[64:79]
	ds_read_b128 v[98:101], v192 offset:57600
	ds_read_b128 v[102:105], v208 offset:12544
	ds_read_b128 v[106:109], v181 offset:8192
	s_waitcnt lgkmcnt(0)
	v_mfma_f32_32x32x16_bf16 v[80:95], v[98:101], v[106:109], v[80:95]
	v_mfma_f32_32x32x16_bf16 v[64:79], v[102:105], v[106:109], v[64:79]
	ds_read_b128 v[98:101], v190 offset:57600
	ds_read_b128 v[102:105], v206 offset:12544
	ds_read_b128 v[106:109], v181 offset:16384
	s_waitcnt lgkmcnt(0)
	v_mfma_f32_32x32x16_bf16 v[80:95], v[98:101], v[106:109], v[80:95]
	v_mfma_f32_32x32x16_bf16 v[64:79], v[102:105], v[106:109], v[64:79]
	ds_read_b128 v[98:101], v173 offset:57600
	ds_read_b128 v[102:105], v202 offset:12544
	ds_read_b128 v[106:109], v181 offset:24576
	s_waitcnt lgkmcnt(0)
	v_mfma_f32_32x32x16_bf16 v[80:95], v[98:101], v[106:109], v[80:95]
	v_add_f32_e32 v98, 0, v219
	v_add_f32_e32 v98, v221, v98
	v_add_f32_e32 v98, v157, v98
	v_add_f32_e32 v98, v220, v98
	v_add_f32_e32 v98, v156, v98
	v_add_f32_e32 v98, v218, v98
	v_add_f32_e32 v98, v154, v98
	v_add_f32_e32 v98, v155, v98
	v_add_f32_e32 v98, v151, v98
	v_add_f32_e32 v98, v153, v98
	v_add_f32_e32 v98, v150, v98
	v_add_f32_e32 v98, v152, v98
	v_mfma_f32_32x32x16_bf16 v[64:79], v[102:105], v[106:109], v[64:79]
	v_exp_f32_e32 v108, v142
	v_add_f32_e32 v98, v147, v98
	v_exp_f32_e32 v109, v143
	v_add_f32_e32 v98, v149, v98
	v_add_f32_e32 v98, v146, v98
	v_add_f32_e32 v98, v148, v98
	v_add_f32_e32 v98, v108, v98
	v_add_f32_e32 v98, v109, v98
	v_add_f32_e32 v98, v110, v98
	v_add_f32_e32 v98, v111, v98
	v_add_f32_e32 v98, v112, v98
	v_add_f32_e32 v98, v113, v98
	v_add_f32_e32 v98, v114, v98
	v_add_f32_e32 v98, v115, v98
	v_add_f32_e32 v98, v116, v98
	v_add_f32_e32 v98, v117, v98
	v_add_f32_e32 v98, v118, v98
	v_add_f32_e32 v98, v119, v98
	v_add_f32_e32 v98, v120, v98
	v_add_f32_e32 v98, v121, v98
	v_add_f32_e32 v98, v122, v98
	v_add_f32_e32 v102, v123, v98
	v_mov_b32_e32 v103, v102
	v_cvt_pk_bf16_f32 v98, v219, v221
	v_cvt_pk_bf16_f32 v99, v157, v220
	v_cvt_pk_bf16_f32 v100, v156, v218
	v_cvt_pk_bf16_f32 v101, v154, v155
	s_nop 1
	v_permlane32_swap_b32_e32 v102, v103
	v_permlane32_swap_b32_e32 v98, v100
	v_permlane32_swap_b32_e32 v99, v101
	v_cvt_pk_bf16_f32 v104, v151, v153
	v_cvt_pk_bf16_f32 v105, v150, v152
	v_cvt_pk_bf16_f32 v106, v147, v149
	v_cvt_pk_bf16_f32 v107, v146, v148
	v_cvt_pk_bf16_f32 v108, v108, v109
	v_cvt_pk_bf16_f32 v109, v110, v111
	v_cvt_pk_bf16_f32 v110, v112, v113
	v_cvt_pk_bf16_f32 v111, v114, v115
	v_cvt_pk_bf16_f32 v112, v116, v117
	v_cvt_pk_bf16_f32 v113, v118, v119
	v_cvt_pk_bf16_f32 v114, v120, v121
	v_cvt_pk_bf16_f32 v115, v122, v123
	s_nop 0
	v_permlane32_swap_b32_e32 v104, v106
	v_permlane32_swap_b32_e32 v105, v107
	v_permlane32_swap_b32_e32 v108, v110
	v_permlane32_swap_b32_e32 v109, v111
	v_permlane32_swap_b32_e32 v112, v114
	v_permlane32_swap_b32_e32 v113, v115
	ds_read_b64_tr_b16 v[116:117], v200 offset:0
	ds_read_b64_tr_b16 v[118:119], v200 offset:0x800
	ds_read_b64_tr_b16 v[120:121], v200 offset:0x1000
	ds_read_b64_tr_b16 v[122:123], v200 offset:0x1800
	ds_read_b64_tr_b16 v[124:125], v200 offset:0x2000
	ds_read_b64_tr_b16 v[126:127], v200 offset:0x2800
	ds_read_b64_tr_b16 v[128:129], v200 offset:0x3000
	ds_read_b64_tr_b16 v[130:131], v200 offset:0x3800
	s_waitcnt lgkmcnt(0)
; #define RESC(al) do { if (__any((al) < 1.f)) { if (hi == 0) al_l[r32] = (al); asm volatile("s_waitcnt lgkmcnt(0)" ::: "memory"); \
;     _Pragma("unroll") for (int d = 0; d < 4; ++d) _Pragma("unroll") for (int r = 0; r < 16; ++r) o[d][r] *= al_l[crow(r, hi)]; } } while (0)
; template <int DQK, int DK1, int LDQ, int LDK, int LDKR, int LDV, int NQL, int SDEPTH>
; __device__ __forceinline__ void attn_core(const AttnArgs& a, char* lds, f32x16 (&o)[4]) {
;     ...
;     pv_d0(o, vb0, pa0, pa1, pa2, pa3); partialSM(pB0, pB1, m_reg, mnB, alB, a.C, a.thr);
;     __syncthreads(); RESC(alB);
	s_nop 0
	v_mfma_f32_32x32x16_bf16 v[48:63], v[98:101], v[116:119], v[48:63]
	ds_read_b64_tr_b16 v[116:117], v200 offset:0x200
	ds_read_b64_tr_b16 v[118:119], v200 offset:0xa00
	v_mfma_f32_32x32x16_bf16 v[48:63], v[104:107], v[120:123], v[48:63]
	ds_read_b64_tr_b16 v[120:121], v200 offset:0x1200
	ds_read_b64_tr_b16 v[122:123], v200 offset:0x1a00
	v_mfma_f32_32x32x16_bf16 v[48:63], v[108:111], v[124:127], v[48:63]
	ds_read_b64_tr_b16 v[124:125], v200 offset:0x2200
	ds_read_b64_tr_b16 v[126:127], v200 offset:0x2a00
	v_mfma_f32_32x32x16_bf16 v[48:63], v[112:115], v[128:131], v[48:63]
	ds_read_b64_tr_b16 v[128:129], v200 offset:0x3200
	ds_read_b64_tr_b16 v[130:131], v200 offset:0x3a00
	s_waitcnt lgkmcnt(6)
	v_mfma_f32_32x32x16_bf16 v[32:47], v[98:101], v[116:119], v[32:47]
	ds_read_b64_tr_b16 v[116:117], v200 offset:0x400
	ds_read_b64_tr_b16 v[118:119], v200 offset:0xc00
	s_waitcnt lgkmcnt(6)
	v_mfma_f32_32x32x16_bf16 v[32:47], v[104:107], v[120:123], v[32:47]
	ds_read_b64_tr_b16 v[120:121], v200 offset:0x1400
	ds_read_b64_tr_b16 v[122:123], v200 offset:0x1c00
	s_waitcnt lgkmcnt(6)
	v_mfma_f32_32x32x16_bf16 v[32:47], v[108:111], v[124:127], v[32:47]
	ds_read_b64_tr_b16 v[124:125], v200 offset:0x2400
	ds_read_b64_tr_b16 v[126:127], v200 offset:0x2c00
	s_waitcnt lgkmcnt(6)
	v_mfma_f32_32x32x16_bf16 v[32:47], v[112:115], v[128:131], v[32:47]
	ds_read_b64_tr_b16 v[128:129], v200 offset:0x3400
	ds_read_b64_tr_b16 v[130:131], v200 offset:0x3c00
	s_waitcnt lgkmcnt(6)
	v_mfma_f32_32x32x16_bf16 v[16:31], v[98:101], v[116:119], v[16:31]
	ds_read_b64_tr_b16 v[116:117], v200 offset:0x600
	ds_read_b64_tr_b16 v[118:119], v200 offset:0xe00
	s_waitcnt lgkmcnt(6)
	v_mfma_f32_32x32x16_bf16 v[16:31], v[104:107], v[120:123], v[16:31]
	ds_read_b64_tr_b16 v[120:121], v200 offset:0x1600
	ds_read_b64_tr_b16 v[122:123], v200 offset:0x1e00
	s_waitcnt lgkmcnt(6)
	v_mfma_f32_32x32x16_bf16 v[16:31], v[108:111], v[124:127], v[16:31]
	ds_read_b64_tr_b16 v[124:125], v200 offset:0x2600
	ds_read_b64_tr_b16 v[126:127], v200 offset:0x2e00
	s_waitcnt lgkmcnt(6)
	v_mfma_f32_32x32x16_bf16 v[16:31], v[112:115], v[128:131], v[16:31]
	ds_read_b64_tr_b16 v[128:129], v200 offset:0x3600
	ds_read_b64_tr_b16 v[130:131], v200 offset:0x3e00
	s_waitcnt lgkmcnt(6)
	v_mfma_f32_32x32x16_bf16 v[0:15], v[98:101], v[116:119], v[0:15]
	v_max_f32_e32 v98, v81, v81
	v_max_f32_e32 v99, v80, v80
	v_max_f32_e32 v98, v99, v98
	v_max3_f32 v98, v98, v82, v83
	v_max3_f32 v98, v98, v84, v85
	v_max3_f32 v98, v98, v86, v87
	v_max3_f32 v98, v98, v88, v89
	v_max3_f32 v98, v98, v90, v91
	v_max3_f32 v98, v98, v92, v93
	s_waitcnt lgkmcnt(4)
	v_mfma_f32_32x32x16_bf16 v[0:15], v[104:107], v[120:123], v[0:15]
	v_max3_f32 v98, v98, v94, v95
	v_max3_f32 v98, v98, v64, v65
	v_max3_f32 v98, v98, v66, v67
	v_max3_f32 v98, v98, v68, v69
	v_max3_f32 v98, v98, v70, v71
	v_max3_f32 v98, v98, v72, v73
	v_max3_f32 v98, v98, v74, v75
	v_max3_f32 v98, v98, v76, v77
	s_waitcnt lgkmcnt(2)
	v_mfma_f32_32x32x16_bf16 v[0:15], v[108:111], v[124:127], v[0:15]
	v_max3_f32 v98, v98, v78, v79
	v_mov_b32_e32 v99, v98
	s_nop 1
	v_permlane32_swap_b32_e32 v98, v99
	v_max_f32_e32 v99, v99, v99
	v_max_f32_e32 v98, v98, v98
	v_max_f32_e32 v98, v98, v99
	v_sub_f32_e32 v99, v98, v204
	v_cmp_ge_f32_e32 vcc, s72, v99
	v_max_f32_e32 v99, v204, v204
	v_max_f32_e32 v99, v99, v98
	s_waitcnt lgkmcnt(0)
	v_mfma_f32_32x32x16_bf16 v[0:15], v[112:115], v[128:131], v[0:15]
	v_sub_f32_e32 v98, v204, v99
	v_mul_f32_e32 v98, 0x3dd53b94, v98
	v_exp_f32_e32 v98, v98
	s_cmp_eq_u64 vcc, exec
	s_cselect_b64 s[14:15], -1, 0
	v_cndmask_b32_e64 v98, v98, 1.0, s[14:15]
	v_cmp_gt_f32_e32 vcc, 1.0, v98
	s_barrier
	s_cbranch_vccz .LBB0_233
	s_and_saveexec_b64 s[20:21], s[12:13]
	s_movk_i32 s37, 0x7fff
	s_movk_i32 s73, 0x47ff
	v_readlane_b32 s68, v255, 18
	ds_write_b32 v165, v98 offset:128
	s_or_b64 exec, exec, s[20:21]
	s_waitcnt lgkmcnt(0)
	v_add_u32_e32 v100, v161, v96
	ds_read_b128 v[104:107], v100 offset:224
	ds_read_b128 v[108:111], v100 offset:192
	ds_read_b128 v[112:115], v100 offset:160
	ds_read_b128 v[116:119], v100 offset:128
	s_waitcnt lgkmcnt(3)
	v_pk_mul_f32 v[60:61], v[60:61], v[104:105]
	s_waitcnt lgkmcnt(2)
	v_pk_mul_f32 v[56:57], v[56:57], v[108:109]
	s_waitcnt lgkmcnt(1)
	v_pk_mul_f32 v[52:53], v[52:53], v[112:113]
	v_pk_mul_f32 v[62:63], v[62:63], v[106:107]
	v_pk_mul_f32 v[58:59], v[58:59], v[110:111]
	v_pk_mul_f32 v[54:55], v[54:55], v[114:115]
	s_waitcnt lgkmcnt(0)
	v_pk_mul_f32 v[50:51], v[50:51], v[118:119]
	v_pk_mul_f32 v[48:49], v[48:49], v[116:117]
	v_pk_mul_f32 v[44:45], v[44:45], v[104:105]
	v_pk_mul_f32 v[40:41], v[40:41], v[108:109]
	v_pk_mul_f32 v[36:37], v[36:37], v[112:113]
	v_pk_mul_f32 v[46:47], v[46:47], v[106:107]
	v_pk_mul_f32 v[42:43], v[42:43], v[110:111]
	v_pk_mul_f32 v[38:39], v[38:39], v[114:115]
	v_pk_mul_f32 v[34:35], v[34:35], v[118:119]
	v_pk_mul_f32 v[32:33], v[32:33], v[116:117]
	v_pk_mul_f32 v[28:29], v[28:29], v[104:105]
	v_pk_mul_f32 v[24:25], v[24:25], v[108:109]
	v_pk_mul_f32 v[20:21], v[20:21], v[112:113]
	v_pk_mul_f32 v[30:31], v[30:31], v[106:107]
	v_pk_mul_f32 v[26:27], v[26:27], v[110:111]
	v_pk_mul_f32 v[22:23], v[22:23], v[114:115]
	v_pk_mul_f32 v[18:19], v[18:19], v[118:119]
	v_pk_mul_f32 v[16:17], v[16:17], v[116:117]
	v_pk_mul_f32 v[12:13], v[12:13], v[104:105]
	v_pk_mul_f32 v[8:9], v[8:9], v[108:109]
	v_pk_mul_f32 v[4:5], v[4:5], v[112:113]
	v_pk_mul_f32 v[14:15], v[14:15], v[106:107]
	v_pk_mul_f32 v[10:11], v[10:11], v[110:111]
	v_pk_mul_f32 v[6:7], v[6:7], v[114:115]
	v_pk_mul_f32 v[2:3], v[2:3], v[118:119]
	v_pk_mul_f32 v[0:1], v[0:1], v[116:117]
	s_branch .LBB0_234

; #define SBAR() __builtin_amdgcn_sched_barrier(0)
; template <int DQK, int DK1, int LDQ, int LDK, int LDKR, int LDV, int NQL, int SDEPTH>
; __device__ __forceinline__ void attn_core(const AttnArgs& a, char* lds, f32x16 (&o)[4]) {
;     ...
;     finishSM(pB0, pB1, alB, l_reg, pa0, pa1, pa2, pa3); SBAR();
;     pv_d0(o, vb0 + SHM_V, pa0, pa1, pa2, pa3);
.LBB0_234:
	v_cndmask_b32_e64 v99, v99, v204, s[14:15]
	v_mul_f32_e32 v99, 0xbdd53b94, v99
	v_fmamk_f32 v80, v80, 0x3dd53b94, v99
	v_fmamk_f32 v81, v81, 0x3dd53b94, v99
	v_fmamk_f32 v100, v82, 0x3dd53b94, v99
	v_exp_f32_e32 v82, v80
	v_fmamk_f32 v101, v84, 0x3dd53b94, v99
	v_exp_f32_e32 v84, v81
	v_fmamk_f32 v83, v83, 0x3dd53b94, v99
	v_exp_f32_e32 v80, v100
	v_fmamk_f32 v64, v64, 0x3dd53b94, v99
	v_exp_f32_e32 v83, v83
	v_fmamk_f32 v104, v85, 0x3dd53b94, v99
	v_fmamk_f32 v113, v94, 0x3dd53b94, v99
	v_fmamk_f32 v94, v75, 0x3dd53b94, v99
	v_exp_f32_e32 v75, v101
	v_exp_f32_e32 v100, v64
	v_add_f32_e32 v64, 0, v82
	v_fmamk_f32 v105, v86, 0x3dd53b94, v99
	v_exp_f32_e32 v81, v104
	v_add_f32_e32 v64, v84, v64
	v_fmamk_f32 v106, v87, 0x3dd53b94, v99
	v_fmamk_f32 v112, v93, 0x3dd53b94, v99
	v_fmamk_f32 v93, v74, 0x3dd53b94, v99
	v_exp_f32_e32 v74, v105
	v_add_f32_e32 v64, v80, v64
	v_fmamk_f32 v107, v88, 0x3dd53b94, v99
	v_fmamk_f32 v114, v95, 0x3dd53b94, v99
	v_fmamk_f32 v95, v76, 0x3dd53b94, v99
	v_exp_f32_e32 v76, v106
	v_add_f32_e32 v64, v83, v64
	v_fmamk_f32 v108, v89, 0x3dd53b94, v99
	v_fmamk_f32 v109, v90, 0x3dd53b94, v99
	v_fmamk_f32 v90, v71, 0x3dd53b94, v99
	v_exp_f32_e32 v71, v107
	v_add_f32_e32 v64, v75, v64
	v_fmamk_f32 v111, v92, 0x3dd53b94, v99
	v_fmamk_f32 v92, v73, 0x3dd53b94, v99
	v_exp_f32_e32 v73, v108
	v_add_f32_e32 v64, v81, v64
	v_fmamk_f32 v110, v91, 0x3dd53b94, v99
	v_fmamk_f32 v88, v69, 0x3dd53b94, v99
	v_exp_f32_e32 v69, v109
	v_add_f32_e32 v64, v74, v64
	v_fmamk_f32 v91, v72, 0x3dd53b94, v99
	v_exp_f32_e32 v72, v110
	v_add_f32_e32 v64, v76, v64
	v_fmamk_f32 v86, v67, 0x3dd53b94, v99
	v_exp_f32_e32 v67, v111
	v_add_f32_e32 v64, v71, v64
	v_fmamk_f32 v89, v70, 0x3dd53b94, v99
	v_exp_f32_e32 v70, v112
	v_add_f32_e32 v64, v73, v64
	v_fmamk_f32 v85, v66, 0x3dd53b94, v99
	v_exp_f32_e32 v66, v113
	v_add_f32_e32 v64, v69, v64
	v_fmamk_f32 v87, v68, 0x3dd53b94, v99
	v_exp_f32_e32 v68, v114
	v_add_f32_e32 v64, v72, v64
	v_fmamk_f32 v65, v65, 0x3dd53b94, v99
	v_add_f32_e32 v64, v67, v64
	v_exp_f32_e32 v101, v65
	v_add_f32_e32 v64, v70, v64
	v_exp_f32_e32 v85, v85
	v_add_f32_e32 v64, v66, v64
	v_exp_f32_e32 v86, v86
	v_add_f32_e32 v64, v68, v64
	v_exp_f32_e32 v87, v87
	v_add_f32_e32 v64, v100, v64
	v_exp_f32_e32 v88, v88
	v_add_f32_e32 v64, v101, v64
	v_exp_f32_e32 v89, v89
	v_add_f32_e32 v64, v85, v64
	v_exp_f32_e32 v90, v90
	v_add_f32_e32 v64, v86, v64
	v_exp_f32_e32 v91, v91
	v_add_f32_e32 v64, v87, v64
	v_exp_f32_e32 v92, v92
	v_add_f32_e32 v64, v88, v64
	v_exp_f32_e32 v93, v93
	v_add_f32_e32 v64, v89, v64
	v_exp_f32_e32 v94, v94
	v_add_f32_e32 v64, v90, v64
	v_fmamk_f32 v77, v77, 0x3dd53b94, v99
	v_exp_f32_e32 v95, v95
	v_add_f32_e32 v64, v91, v64
	v_fmamk_f32 v78, v78, 0x3dd53b94, v99
	v_exp_f32_e32 v104, v77
	v_add_f32_e32 v64, v92, v64
	v_fmac_f32_e32 v99, 0x3dd53b94, v79
	v_exp_f32_e32 v105, v78
	v_add_f32_e32 v64, v93, v64
	v_exp_f32_e32 v99, v99
	v_add_f32_e32 v64, v94, v64
	v_add_f32_e32 v64, v95, v64
	v_add_f32_e32 v64, v104, v64
	v_add_f32_e32 v64, v105, v64
	v_add_f32_e32 v64, v99, v64
	v_mov_b32_e32 v65, v64
	s_nop 1
	v_permlane32_swap_b32_e32 v64, v65
	v_cvt_pk_bf16_f32 v78, v82, v84
	v_cvt_pk_bf16_f32 v79, v80, v83
	v_cvt_pk_bf16_f32 v80, v75, v81
	v_cvt_pk_bf16_f32 v81, v74, v76
	v_cvt_pk_bf16_f32 v74, v71, v73
	v_cvt_pk_bf16_f32 v75, v69, v72
	v_cvt_pk_bf16_f32 v76, v67, v70
	v_cvt_pk_bf16_f32 v77, v66, v68
	v_cvt_pk_bf16_f32 v66, v100, v101
	v_cvt_pk_bf16_f32 v67, v85, v86
	v_cvt_pk_bf16_f32 v68, v87, v88
	v_cvt_pk_bf16_f32 v69, v89, v90
	v_cvt_pk_bf16_f32 v70, v91, v92
	v_cvt_pk_bf16_f32 v71, v93, v94
	v_cvt_pk_bf16_f32 v72, v95, v104
	v_cvt_pk_bf16_f32 v73, v105, v99
	s_nop 0
	v_permlane32_swap_b32_e32 v78, v80
	v_permlane32_swap_b32_e32 v79, v81
	v_permlane32_swap_b32_e32 v74, v76
	v_permlane32_swap_b32_e32 v75, v77
	v_permlane32_swap_b32_e32 v66, v68
	v_permlane32_swap_b32_e32 v67, v69
	v_permlane32_swap_b32_e32 v70, v72
	v_permlane32_swap_b32_e32 v71, v73
	ds_read_b64_tr_b16 v[82:83], v169 offset:0
	ds_read_b64_tr_b16 v[84:85], v169 offset:0x800
	ds_read_b64_tr_b16 v[86:87], v169 offset:0x1000
	ds_read_b64_tr_b16 v[88:89], v169 offset:0x1800
	ds_read_b64_tr_b16 v[90:91], v169 offset:0x2000
	ds_read_b64_tr_b16 v[92:93], v169 offset:0x2800
	ds_read_b64_tr_b16 v[104:105], v169 offset:0x3000
	ds_read_b64_tr_b16 v[106:107], v169 offset:0x3800
	s_waitcnt lgkmcnt(0)
	s_nop 0
	v_mfma_f32_32x32x16_bf16 v[48:63], v[78:81], v[82:85], v[48:63]
	ds_read_b64_tr_b16 v[82:83], v169 offset:0x200
	ds_read_b64_tr_b16 v[84:85], v169 offset:0xa00
	v_mfma_f32_32x32x16_bf16 v[48:63], v[74:77], v[86:89], v[48:63]
	ds_read_b64_tr_b16 v[86:87], v169 offset:0x1200
	ds_read_b64_tr_b16 v[88:89], v169 offset:0x1a00
	v_mfma_f32_32x32x16_bf16 v[48:63], v[66:69], v[90:93], v[48:63]
	ds_read_b64_tr_b16 v[90:91], v169 offset:0x2200
	ds_read_b64_tr_b16 v[92:93], v169 offset:0x2a00
	v_mfma_f32_32x32x16_bf16 v[48:63], v[70:73], v[104:107], v[48:63]
	ds_read_b64_tr_b16 v[104:105], v169 offset:0x3200
	ds_read_b64_tr_b16 v[106:107], v169 offset:0x3a00
	s_waitcnt lgkmcnt(6)
	v_mfma_f32_32x32x16_bf16 v[32:47], v[78:81], v[82:85], v[32:47]
	ds_read_b64_tr_b16 v[82:83], v169 offset:0x400
	ds_read_b64_tr_b16 v[84:85], v169 offset:0xc00
	s_waitcnt lgkmcnt(6)
	v_mfma_f32_32x32x16_bf16 v[32:47], v[74:77], v[86:89], v[32:47]
	ds_read_b64_tr_b16 v[86:87], v169 offset:0x1400
	ds_read_b64_tr_b16 v[88:89], v169 offset:0x1c00
	s_waitcnt lgkmcnt(6)
	v_mfma_f32_32x32x16_bf16 v[32:47], v[66:69], v[90:93], v[32:47]
	ds_read_b64_tr_b16 v[90:91], v169 offset:0x2400
	ds_read_b64_tr_b16 v[92:93], v169 offset:0x2c00
	s_waitcnt lgkmcnt(6)
	v_mfma_f32_32x32x16_bf16 v[32:47], v[70:73], v[104:107], v[32:47]
	ds_read_b64_tr_b16 v[104:105], v169 offset:0x3400
	ds_read_b64_tr_b16 v[106:107], v169 offset:0x3c00
	s_waitcnt lgkmcnt(6)
	v_mfma_f32_32x32x16_bf16 v[16:31], v[78:81], v[82:85], v[16:31]
	ds_read_b64_tr_b16 v[82:83], v169 offset:0x600
	ds_read_b64_tr_b16 v[84:85], v169 offset:0xe00
	s_waitcnt lgkmcnt(6)
	v_mfma_f32_32x32x16_bf16 v[16:31], v[74:77], v[86:89], v[16:31]
	ds_read_b64_tr_b16 v[86:87], v169 offset:0x1600
	ds_read_b64_tr_b16 v[88:89], v169 offset:0x1e00
	s_waitcnt lgkmcnt(6)
	v_mfma_f32_32x32x16_bf16 v[16:31], v[66:69], v[90:93], v[16:31]
	ds_read_b64_tr_b16 v[90:91], v169 offset:0x2600
	ds_read_b64_tr_b16 v[92:93], v169 offset:0x2e00
	s_waitcnt lgkmcnt(6)
	v_mfma_f32_32x32x16_bf16 v[16:31], v[70:73], v[104:107], v[16:31]
	ds_read_b64_tr_b16 v[104:105], v169 offset:0x3600
	ds_read_b64_tr_b16 v[106:107], v169 offset:0x3e00
	s_waitcnt lgkmcnt(6)
	v_mfma_f32_32x32x16_bf16 v[0:15], v[78:81], v[82:85], v[0:15]
	s_waitcnt lgkmcnt(4)
	v_mfma_f32_32x32x16_bf16 v[0:15], v[74:77], v[86:89], v[0:15]
	s_waitcnt lgkmcnt(2)
	v_mfma_f32_32x32x16_bf16 v[0:15], v[66:69], v[90:93], v[0:15]
	s_waitcnt lgkmcnt(0)
	v_mfma_f32_32x32x16_bf16 v[0:15], v[70:73], v[104:107], v[0:15]
	s_and_saveexec_b64 s[14:15], s[12:13]
	s_cbranch_execz .LBB0_200
; __device__ __forceinline__ void finishSM(f32x16& p0, f32x16& p1, float alpha, float& l_reg, bf16x8& pa0, bf16x8& pa1, bf16x8& pa2, bf16x8& pa3) {
;     ...
;     { auto rr = __builtin_amdgcn_permlane32_swap(__float_as_uint(ps), __float_as_uint(ps), false, false);
;       ps = __uint_as_float(rr[0]) + __uint_as_float(rr[1]); }
;     l_reg = l_reg * alpha + ps;
; template <int DQK, int DK1, int LDQ, int LDK, int LDKR, int LDV, int NQL, int SDEPTH>
; __device__ __forceinline__ void attn_core(const AttnArgs& a, char* lds, f32x16 (&o)[4]) {
;     ...
;     if (hi == 0) li_l[r32] = l_reg; asm volatile("s_waitcnt lgkmcnt(0)" ::: "memory");
	v_add_f32_e32 v66, v102, v103
	v_fmac_f32_e32 v66, v182, v224
	v_add_f32_e32 v64, v64, v65
	v_fmac_f32_e32 v64, v66, v98
	ds_write_b32 v165, v64
	s_branch .LBB0_200
